# scan: outputs reduced 4 steps at a time (reduce-scatter), first-step LDS reads issued before staging
# speedup vs baseline: 1.0057x; 1.0057x over previous
; __device__ __forceinline__ int bid_() { int b = blockIdx.x; asm volatile("" : "+s"(b)); return b; }
; __device__ __forceinline__ void phase_scan(CParams& P, LAS unsigned char* lds) {
;     ...
;     const int bx_ = bid_(); const int vcu_ = (nb_ % 8 == 0) ? (bx_ % 8) * (nb_ / 8) + bx_ / 8 : bx_;
;     for (int task = vcu_; task < GSEQ * 8 * 2 * 2; task += nb_) {
;         const int rowhalf = task & 1, dir = (task >> 1) & 1, h = (task >> 2) & 7, s = task >> 5;
;         float* OUT = (float*)(P.ws + WS_P2) + (size_t)dir * TG * 512;
;         __syncthreads();
;         if (wid >= 4) {
;             const int ltid = tid - 256; f16x8 v[6];
;     ...
;             SC_GLOAD(0); SC_WRITE(0); SC_GLOAD(1);
; #pragma unroll 1
;             for (int c = 0; c < NCH; ++c) {
;                 __syncthreads();
;                 if (c + 1 < NCH) { SC_WRITE(c + 1); if (c + 2 < NCH) SC_GLOAD(c + 2); }
;             }
;             __syncthreads();
;     ...
;         } else {
;             const int rl = lane >> 3, oct = lane & 7, rloc = wid * 8 + rl;
;             __builtin_amdgcn_s_setprio(3);
;             f32x4 s0 = {0.f, 0.f, 0.f, 0.f}, s1 = {0.f, 0.f, 0.f, 0.f};
;             float* op = OUT + ((size_t)s * SEQ + (dir ? SEQ - 1 : 0)) * 512 + h * 64 + rowhalf * 32 + rloc; const long ostep = dir ? -512 : 512;
.LBB0_235:
	s_andn2_b64 vcc, exec, s[4:5]
	s_cbranch_vccnz .LBB0_627
	s_cmp_gt_i32 s14, 8
	s_mov_b64 s[4:5], -1
	s_cbranch_scc0 .LBB0_606
	s_waitcnt vmcnt(0)
	s_and_b32 s4, s2, 7
	s_lshl_b32 s4, s4, 5
	s_lshr_b32 s5, s2, 3
	s_add_i32 s4, s4, s5
	s_and_b32 s8, s4, 1
	s_bfe_u32 s5, s4, 0x10001
	s_bfe_u32 s6, s4, 0x30002
	s_lshr_b32 s7, s4, 5
	s_mul_i32 s9, s7, 0xc00000
	s_mul_i32 s12, s6, 0x180
	s_add_i32 s9, s9, s12
	s_add_i32 s12, s9, 0x1a000000
	s_add_u32 s40, s22, s12
	s_addc_u32 s41, s23, 0
	s_mul_i32 s12, s5, 0x6000000
	s_add_i32 s12, s12, s9
	s_add_i32 s12, s12, 0x20000000
	s_add_u32 s42, s22, s12
	s_addc_u32 s43, s23, 0
	s_lshl_b32 s12, s7, 22
	s_lshl_b32 s15, s6, 7
	s_add_i32 s12, s12, s15
	s_lshl_b32 s15, s8, 6
	s_add_i32 s12, s12, s15
	s_add_i32 s12, s12, 0x2e000000
	s_add_u32 s44, s22, s12
	s_addc_u32 s45, s23, 0
	s_lshl_b32 s12, s7, 23
	s_lshl_b32 s15, s6, 8
	s_add_i32 s12, s12, s15
	s_lshl_b32 s15, s8, 7
	s_add_i32 s12, s12, s15
	s_lshl_b32 s15, s5, 26
	s_add_i32 s12, s12, s15
	s_add_i32 s12, s12, 0x8000000
	s_add_u32 s10, s22, s12
	s_addc_u32 s11, s23, 0
	s_cmp_eq_u32 s5, 0
	s_cselect_b32 s46, 0, 0xfff
	s_mov_b32 s47, 0xfffe8000
	s_cselect_b32 s48, 0x18000, s47
	s_cselect_b32 s49, 0, -1
	s_mov_b32 s47, 0xffff8000
	s_cselect_b32 s36, 0x8000, s47
	s_cselect_b32 s37, 0, -1
	s_mov_b32 s47, 0xffffe000
	s_cselect_b32 s13, 0x2000, s47
	s_mov_b32 s50, 0xaaaaaaaa
	s_mov_b32 s51, 0xaaaaaaaa
	s_mov_b32 s52, 0xcccccccc
	s_mov_b32 s53, 0xcccccccc
	v_lshrrev_b32_e32 v0, 6, v222
	v_and_b32_e32 v6, 15, v222
	v_readfirstlane_b32 s28, v0
	v_lshrrev_b32_e32 v7, 4, v222
	s_cmp_lt_u32 s28, 4
	s_cselect_b32 s36, s48, s36
	s_cselect_b32 s37, s49, s37
	v_xor_b32_e32 v1, s46, v7
	v_mul_u32_u24_e32 v1, 0xc00, v1
	v_lshlrev_b32_e32 v64, 4, v6
	v_add_u32_e32 v130, v1, v64
	v_mov_b32_e32 v131, 0
	v_and_b32_e32 v1, 8, v6
	v_lshlrev_b32_e32 v1, 4, v1
	v_add_u32_e32 v128, v130, v1
	v_mov_b32_e32 v129, 0
	v_lshl_add_u64 v[74:75], s[40:41], 0, v[128:129]
	v_lshl_add_u64 v[76:77], s[42:43], 0, v[130:131]
	v_mul_u32_u24_e32 v0, 0x500, v7
	v_and_b32_e32 v1, 7, v6
	v_lshlrev_b32_e32 v1, 5, v1
	v_add_u32_e32 v0, v0, v1
	v_and_b32_e32 v1, 8, v6
	v_lshlrev_b32_e32 v127, 7, v1
	v_sub_u32_e32 v127, 0x400, v127
	v_add_u32_e32 v100, v0, v127
	v_lshlrev_b32_e32 v127, 5, v1
	v_add_u32_e32 v127, 0x100, v127
	v_add_u32_e32 v101, v0, v127
	s_cmp_lt_u32 s28, 4
	s_cbranch_scc0 .Lsc_roleV
	v_lshrrev_b32_e32 v0, 3, v222
	v_and_b32_e32 v1, 7, v222
	v_xor_b32_e32 v127, s46, v0
	v_mul_u32_u24_e32 v127, 0xc00, v127
	v_lshlrev_b32_e32 v128, 4, v1
	v_add_u32_e32 v128, v127, v128
	v_add_u32_e32 v128, 0x100, v128
	v_mov_b32_e32 v129, 0
	v_lshl_add_u64 v[78:79], s[42:43], 0, v[128:129]
	v_mul_u32_u24_e32 v0, 0x500, v0
	v_lshlrev_b32_e32 v1, 5, v1
	v_add_u32_e32 v0, v0, v1
	v_add_u32_e32 v102, 0x300, v0
	s_branch .Lsc_roleDone

; __device__ __forceinline__ void phase_scan(CParams& P, LAS unsigned char* lds) {
;     ...
;             SC_GLOAD(0); SC_WRITE(0); SC_GLOAD(1);
;     ...
;             const int rl = lane >> 3, oct = lane & 7, rloc = wid * 8 + rl;
;             __builtin_amdgcn_s_setprio(3);
;             f32x4 s0 = {0.f, 0.f, 0.f, 0.f}, s1 = {0.f, 0.f, 0.f, 0.f};
;             float* op = OUT + ((size_t)s * SEQ + (dir ? SEQ - 1 : 0)) * 512 + h * 64 + rowhalf * 32 + rloc; const long ostep = dir ? -512 : 512;
.Lsc_roleDone:
	v_lshlrev_b32_e32 v70, 4, v6
	v_lshlrev_b32_e32 v0, 7, v7
	v_add_u32_e32 v71, 0xa000, v0
	v_and_b32_e32 v0, 3, v6
	v_xor_b32_e32 v0, s46, v0
	v_lshlrev_b32_e32 v0, 11, v0
	v_lshl_add_u32 v72, v7, 2, v0
	v_mov_b32_e32 v2, 0
	v_mov_b32_e32 v3, 0
	v_mov_b32_e32 v4, 0
	v_mov_b32_e32 v5, 0
	global_load_dwordx4 v[80:83], v[74:75], off
	global_load_dwordx4 v[84:87], v[76:77], off
	v_lshl_add_u64 v[74:75], v[74:75], 0, s[48:49]
	v_lshl_add_u64 v[76:77], v[76:77], 0, s[48:49]
	s_cmp_lt_u32 s28, 6
	s_cbranch_scc0 .Lsc_noC1
	global_load_dwordx4 v[88:91], v[78:79], off
	v_lshl_add_u64 v[78:79], v[78:79], 0, s[36:37]

; #define LAS __attribute__((address_space(3)))
; __device__ __forceinline__ void phase_scan(CParams& P, LAS unsigned char* lds) {
;     ...
;                 if (c + 1 < NCH) { SC_WRITE(c + 1); if (c + 2 < NCH) SC_GLOAD(c + 2); }
;     ...
;             for (int c = 0; c < NCH; ++c) {
;                 __syncthreads();
;                 const LAS float* base = lf + (c & 1) * BUFF + 8 * oct;
;                 SC_LOAD(A, base);
.Lsc_chunk:
	s_waitcnt lgkmcnt(0)
	s_barrier
	v_add_u32_e32 v73, s14, v70
	v_add_u32_e32 v69, s14, v71
	ds_read_b128 v[48:51], v69 offset:0
	ds_read_b128 v[8:11], v73 offset:0
	ds_read_b128 v[16:19], v73 offset:512
	ds_read_b128 v[12:15], v73 offset:256
	ds_read_b128 v[20:23], v73 offset:768
	ds_read_b128 v[24:27], v73 offset:1024
	ds_read_b128 v[28:31], v73 offset:1280
	ds_read_b128 v[36:39], v73 offset:1792
	ds_read_b128 v[32:35], v73 offset:1536
	ds_read_b128 v[40:43], v73 offset:2048
	ds_read_b128 v[44:47], v73 offset:2304
	s_cmp_ge_u32 s12, 0x7f
	s_cbranch_scc1 .Lsc_noload
	s_cmp_eq_u32 s12, 0
	s_cbranch_scc0 .Lsc_w8
	s_waitcnt vmcnt(0)

; #define LAS __attribute__((address_space(3)))
; __device__ __forceinline__ void phase_scan(CParams& P, LAS unsigned char* lds) {
;     ...
;             f32x4 Ar0, Ar1, Aw0, Aw1, Ak0, Ak1, Aq0, Aq1, Ab0, Ab1, Br0, Br1, Bw0, Bw1, Bk0, Bk1, Bq0, Bq1, Bb0, Bb1; float Avv, Bvv;
; #pragma unroll 1
;             for (int c = 0; c < NCH; ++c) {
;                 __syncthreads();
;                 const LAS float* base = lf + (c & 1) * BUFF + 8 * oct;
;                 SC_LOAD(A, base);
; #pragma unroll 2
;                 for (int j = 0; j < CH; j += 2) { const LAS float* sp = base + j * STEPF;
;                     SC_LOAD(B, sp + STEPF); SC_STEP(A);
;                     SC_LOAD(A, sp + 2 * STEPF);
;                     SC_STEP(B); }
.Lsc_noC5:
.Lsc_noload:
	s_waitcnt lgkmcnt(0)
	v_pk_mul_f32 v[56:57], v[2:3], v[8:9]
	v_pk_fma_f32 v[56:57], v[4:5], v[10:11], v[56:57]
	v_pk_mul_f32 v[58:59], v[16:17], v[48:49] op_sel_hi:[1,0]
	v_add_f32_e32 v66, v56, v57
	v_pk_mul_f32 v[60:61], v[18:19], v[48:49] op_sel_hi:[1,0]
	v_pk_fma_f32 v[58:59], v[2:3], v[12:13], v[58:59]
	v_add_f32_dpp v66, v66, v66 quad_perm:[1,0,3,2] row_mask:0xf bank_mask:0xf bound_ctrl:1
	v_pk_fma_f32 v[60:61], v[4:5], v[14:15], v[60:61]
	ds_read_b128 v[106:109], v73 offset:2560
	v_add_f32_dpp v66, v66, v66 quad_perm:[2,3,0,1] row_mask:0xf bank_mask:0xf bound_ctrl:1
	ds_read_b128 v[114:117], v73 offset:3072
	ds_read_b128 v[110:113], v73 offset:2816
	v_add_f32_dpp v66, v66, v66 row_half_mirror row_mask:0xf bank_mask:0xf bound_ctrl:1
	ds_read_b128 v[118:121], v73 offset:3328
	ds_read_b128 v[122:125], v73 offset:3584
	v_add_f32_dpp v66, v66, v66 row_mirror row_mask:0xf bank_mask:0xf bound_ctrl:1
	v_pk_fma_f32 v[2:3], v[20:21], v[66:67], v[58:59] op_sel_hi:[1,0,1]
	v_pk_fma_f32 v[4:5], v[22:23], v[66:67], v[60:61] op_sel_hi:[1,0,1]
	s_waitcnt lgkmcnt(5)
	v_pk_mul_f32 v[56:57], v[2:3], v[28:29]
	v_pk_mul_f32 v[62:63], v[2:3], v[24:25]
	v_pk_fma_f32 v[56:57], v[4:5], v[30:31], v[56:57]
	v_pk_fma_f32 v[62:63], v[4:5], v[26:27], v[62:63]
	v_pk_mul_f32 v[58:59], v[36:37], v[48:49] op_sel:[0,1] op_sel_hi:[1,1]
	v_add_f32_e32 v66, v56, v57
	v_pk_mul_f32 v[60:61], v[38:39], v[48:49] op_sel:[0,1] op_sel_hi:[1,1]
	v_add_f32_e32 v132, v62, v63
	v_pk_fma_f32 v[58:59], v[2:3], v[32:33], v[58:59]
	v_add_f32_dpp v66, v66, v66 quad_perm:[1,0,3,2] row_mask:0xf bank_mask:0xf bound_ctrl:1
	v_pk_fma_f32 v[60:61], v[4:5], v[34:35], v[60:61]
	ds_read_b128 v[8:11], v73 offset:3840
	v_add_f32_dpp v66, v66, v66 quad_perm:[2,3,0,1] row_mask:0xf bank_mask:0xf bound_ctrl:1
	ds_read_b128 v[16:19], v73 offset:4352
	ds_read_b128 v[12:15], v73 offset:4096
	v_add_f32_dpp v66, v66, v66 row_half_mirror row_mask:0xf bank_mask:0xf bound_ctrl:1
	ds_read_b128 v[20:23], v73 offset:4608
	ds_read_b128 v[24:27], v73 offset:4864
	v_add_f32_dpp v66, v66, v66 row_mirror row_mask:0xf bank_mask:0xf bound_ctrl:1
	ds_read_b128 v[52:55], v69 offset:16
	v_pk_fma_f32 v[2:3], v[40:41], v[66:67], v[58:59] op_sel_hi:[1,0,1]
	v_pk_fma_f32 v[4:5], v[42:43], v[66:67], v[60:61] op_sel_hi:[1,0,1]
	s_waitcnt lgkmcnt(6)
	v_pk_mul_f32 v[56:57], v[2:3], v[106:107]
	v_pk_mul_f32 v[62:63], v[2:3], v[44:45]
	v_pk_fma_f32 v[56:57], v[4:5], v[108:109], v[56:57]
	v_pk_fma_f32 v[62:63], v[4:5], v[46:47], v[62:63]
	v_pk_mul_f32 v[58:59], v[114:115], v[50:51] op_sel_hi:[1,0]
	v_add_f32_e32 v66, v56, v57
	v_pk_mul_f32 v[60:61], v[116:117], v[50:51] op_sel_hi:[1,0]
	v_add_f32_e32 v133, v62, v63
	v_pk_fma_f32 v[58:59], v[2:3], v[110:111], v[58:59]
	v_add_f32_dpp v66, v66, v66 quad_perm:[1,0,3,2] row_mask:0xf bank_mask:0xf bound_ctrl:1
	v_pk_fma_f32 v[60:61], v[4:5], v[112:113], v[60:61]
	ds_read_b128 v[28:31], v73 offset:5120
	v_add_f32_dpp v66, v66, v66 quad_perm:[2,3,0,1] row_mask:0xf bank_mask:0xf bound_ctrl:1
	ds_read_b128 v[36:39], v73 offset:5632
	ds_read_b128 v[32:35], v73 offset:5376
	v_add_f32_dpp v66, v66, v66 row_half_mirror row_mask:0xf bank_mask:0xf bound_ctrl:1
	ds_read_b128 v[40:43], v73 offset:5888
	ds_read_b128 v[44:47], v73 offset:6144
	v_add_f32_dpp v66, v66, v66 row_mirror row_mask:0xf bank_mask:0xf bound_ctrl:1
	v_pk_fma_f32 v[2:3], v[118:119], v[66:67], v[58:59] op_sel_hi:[1,0,1]
	v_pk_fma_f32 v[4:5], v[120:121], v[66:67], v[60:61] op_sel_hi:[1,0,1]
	s_waitcnt lgkmcnt(6)
	v_pk_mul_f32 v[56:57], v[2:3], v[8:9]
	v_pk_mul_f32 v[62:63], v[2:3], v[122:123]
	v_pk_fma_f32 v[56:57], v[4:5], v[10:11], v[56:57]
	v_pk_fma_f32 v[62:63], v[4:5], v[124:125], v[62:63]
	v_pk_mul_f32 v[58:59], v[16:17], v[50:51] op_sel:[0,1] op_sel_hi:[1,1]
	v_add_f32_e32 v66, v56, v57
	v_pk_mul_f32 v[60:61], v[18:19], v[50:51] op_sel:[0,1] op_sel_hi:[1,1]
	v_add_f32_e32 v134, v62, v63
	v_pk_fma_f32 v[58:59], v[2:3], v[12:13], v[58:59]
	v_add_f32_dpp v66, v66, v66 quad_perm:[1,0,3,2] row_mask:0xf bank_mask:0xf bound_ctrl:1
	v_pk_fma_f32 v[60:61], v[4:5], v[14:15], v[60:61]
	ds_read_b128 v[106:109], v73 offset:6400
	v_add_f32_dpp v66, v66, v66 quad_perm:[2,3,0,1] row_mask:0xf bank_mask:0xf bound_ctrl:1
	ds_read_b128 v[114:117], v73 offset:6912
	ds_read_b128 v[110:113], v73 offset:6656
	v_add_f32_dpp v66, v66, v66 row_half_mirror row_mask:0xf bank_mask:0xf bound_ctrl:1
	ds_read_b128 v[118:121], v73 offset:7168
	ds_read_b128 v[122:125], v73 offset:7424
	v_add_f32_dpp v66, v66, v66 row_mirror row_mask:0xf bank_mask:0xf bound_ctrl:1
	v_pk_fma_f32 v[2:3], v[20:21], v[66:67], v[58:59] op_sel_hi:[1,0,1]
	v_pk_fma_f32 v[4:5], v[22:23], v[66:67], v[60:61] op_sel_hi:[1,0,1]
	s_waitcnt lgkmcnt(5)
	v_pk_mul_f32 v[56:57], v[2:3], v[28:29]
	v_pk_mul_f32 v[62:63], v[2:3], v[24:25]
	v_pk_fma_f32 v[56:57], v[4:5], v[30:31], v[56:57]
	v_pk_fma_f32 v[62:63], v[4:5], v[26:27], v[62:63]
	v_pk_mul_f32 v[58:59], v[36:37], v[52:53] op_sel_hi:[1,0]
	v_add_f32_e32 v66, v56, v57
	v_pk_mul_f32 v[60:61], v[38:39], v[52:53] op_sel_hi:[1,0]
	v_add_f32_e32 v135, v62, v63
	v_pk_fma_f32 v[58:59], v[2:3], v[32:33], v[58:59]
	v_add_f32_dpp v66, v66, v66 quad_perm:[1,0,3,2] row_mask:0xf bank_mask:0xf bound_ctrl:1
	v_pk_fma_f32 v[60:61], v[4:5], v[34:35], v[60:61]
	v_cndmask_b32_e64 v136, v132, v133, s[50:51]
	ds_read_b128 v[8:11], v73 offset:7680
	v_add_f32_dpp v66, v66, v66 quad_perm:[2,3,0,1] row_mask:0xf bank_mask:0xf bound_ctrl:1
	ds_read_b128 v[16:19], v73 offset:8192
	v_cndmask_b32_e64 v137, v133, v132, s[50:51]
	ds_read_b128 v[12:15], v73 offset:7936
	v_add_f32_dpp v66, v66, v66 row_half_mirror row_mask:0xf bank_mask:0xf bound_ctrl:1
	ds_read_b128 v[20:23], v73 offset:8448
	v_cndmask_b32_e64 v138, v134, v135, s[50:51]
	ds_read_b128 v[24:27], v73 offset:8704
	v_add_f32_dpp v66, v66, v66 row_mirror row_mask:0xf bank_mask:0xf bound_ctrl:1
	v_cndmask_b32_e64 v139, v135, v134, s[50:51]
	v_pk_fma_f32 v[2:3], v[40:41], v[66:67], v[58:59] op_sel_hi:[1,0,1]
	v_pk_fma_f32 v[4:5], v[42:43], v[66:67], v[60:61] op_sel_hi:[1,0,1]
	s_waitcnt lgkmcnt(5)
; #define LAS __attribute__((address_space(3)))
; __device__ __forceinline__ void phase_scan(CParams& P, LAS unsigned char* lds) {
;     ...
;             f32x4 Ar0, Ar1, Aw0, Aw1, Ak0, Ak1, Aq0, Aq1, Ab0, Ab1, Br0, Br1, Bw0, Bw1, Bk0, Bk1, Bq0, Bq1, Bb0, Bb1; float Avv, Bvv;
; #pragma unroll 1
;             for (int c = 0; c < NCH; ++c) {
;                 __syncthreads();
;                 const LAS float* base = lf + (c & 1) * BUFF + 8 * oct;
;                 SC_LOAD(A, base);
; #pragma unroll 2
;                 for (int j = 0; j < CH; j += 2) { const LAS float* sp = base + j * STEPF;
;                     SC_LOAD(B, sp + STEPF); SC_STEP(A);
;                     SC_LOAD(A, sp + 2 * STEPF);
;                     SC_STEP(B); }
	v_pk_mul_f32 v[56:57], v[2:3], v[106:107]
	v_pk_mul_f32 v[62:63], v[2:3], v[44:45]
	v_pk_fma_f32 v[56:57], v[4:5], v[108:109], v[56:57]
	v_pk_fma_f32 v[62:63], v[4:5], v[46:47], v[62:63]
	v_pk_mul_f32 v[58:59], v[114:115], v[52:53] op_sel:[0,1] op_sel_hi:[1,1]
	v_add_f32_e32 v66, v56, v57
	v_pk_mul_f32 v[60:61], v[116:117], v[52:53] op_sel:[0,1] op_sel_hi:[1,1]
	v_add_f32_e32 v132, v62, v63
	v_pk_fma_f32 v[58:59], v[2:3], v[110:111], v[58:59]
	v_add_f32_dpp v66, v66, v66 quad_perm:[1,0,3,2] row_mask:0xf bank_mask:0xf bound_ctrl:1
	v_pk_fma_f32 v[60:61], v[4:5], v[112:113], v[60:61]
	v_add_f32_dpp v140, v137, v136 quad_perm:[1,0,3,2] row_mask:0xf bank_mask:0xf bound_ctrl:1
	ds_read_b128 v[28:31], v73 offset:8960
	v_add_f32_dpp v66, v66, v66 quad_perm:[2,3,0,1] row_mask:0xf bank_mask:0xf bound_ctrl:1
	ds_read_b128 v[36:39], v73 offset:9472
	v_add_f32_dpp v141, v139, v138 quad_perm:[1,0,3,2] row_mask:0xf bank_mask:0xf bound_ctrl:1
	ds_read_b128 v[32:35], v73 offset:9216
	v_add_f32_dpp v66, v66, v66 row_half_mirror row_mask:0xf bank_mask:0xf bound_ctrl:1
	ds_read_b128 v[40:43], v73 offset:9728
	v_cndmask_b32_e64 v142, v140, v141, s[52:53]
	ds_read_b128 v[44:47], v73 offset:9984
	v_add_f32_dpp v66, v66, v66 row_mirror row_mask:0xf bank_mask:0xf bound_ctrl:1
	ds_read_b128 v[48:51], v69 offset:32
	v_cndmask_b32_e64 v143, v141, v140, s[52:53]
	v_pk_fma_f32 v[2:3], v[118:119], v[66:67], v[58:59] op_sel_hi:[1,0,1]
	v_pk_fma_f32 v[4:5], v[120:121], v[66:67], v[60:61] op_sel_hi:[1,0,1]
	s_waitcnt lgkmcnt(6)
	v_pk_mul_f32 v[56:57], v[2:3], v[8:9]
	v_pk_mul_f32 v[62:63], v[2:3], v[122:123]
	v_pk_fma_f32 v[56:57], v[4:5], v[10:11], v[56:57]
	v_pk_fma_f32 v[62:63], v[4:5], v[124:125], v[62:63]
	v_pk_mul_f32 v[58:59], v[16:17], v[54:55] op_sel_hi:[1,0]
	v_add_f32_e32 v66, v56, v57
	v_pk_mul_f32 v[60:61], v[18:19], v[54:55] op_sel_hi:[1,0]
	v_add_f32_e32 v133, v62, v63
	v_pk_fma_f32 v[58:59], v[2:3], v[12:13], v[58:59]
	v_add_f32_dpp v66, v66, v66 quad_perm:[1,0,3,2] row_mask:0xf bank_mask:0xf bound_ctrl:1
	v_pk_fma_f32 v[60:61], v[4:5], v[14:15], v[60:61]
	v_add_f32_dpp v144, v143, v142 quad_perm:[2,3,0,1] row_mask:0xf bank_mask:0xf bound_ctrl:1
	ds_read_b128 v[106:109], v73 offset:10240
	v_add_f32_dpp v66, v66, v66 quad_perm:[2,3,0,1] row_mask:0xf bank_mask:0xf bound_ctrl:1
	ds_read_b128 v[114:117], v73 offset:10752
	v_add_f32_dpp v144, v144, v144 row_ror:4 row_mask:0xf bank_mask:0xf bound_ctrl:1
	ds_read_b128 v[110:113], v73 offset:10496
	v_add_f32_dpp v66, v66, v66 row_half_mirror row_mask:0xf bank_mask:0xf bound_ctrl:1
	ds_read_b128 v[118:121], v73 offset:11008
	v_add_f32_dpp v144, v144, v144 row_ror:8 row_mask:0xf bank_mask:0xf bound_ctrl:1
	ds_read_b128 v[122:125], v73 offset:11264
	v_add_f32_dpp v66, v66, v66 row_mirror row_mask:0xf bank_mask:0xf bound_ctrl:1
	global_store_dword v72, v144, s[10:11]
	v_add_u32_e32 v72, s13, v72
	v_pk_fma_f32 v[2:3], v[20:21], v[66:67], v[58:59] op_sel_hi:[1,0,1]
	v_pk_fma_f32 v[4:5], v[22:23], v[66:67], v[60:61] op_sel_hi:[1,0,1]
	s_waitcnt lgkmcnt(6)
	v_pk_mul_f32 v[56:57], v[2:3], v[28:29]
	v_pk_mul_f32 v[62:63], v[2:3], v[24:25]
	v_pk_fma_f32 v[56:57], v[4:5], v[30:31], v[56:57]
	v_pk_fma_f32 v[62:63], v[4:5], v[26:27], v[62:63]
	v_pk_mul_f32 v[58:59], v[36:37], v[54:55] op_sel:[0,1] op_sel_hi:[1,1]
	v_add_f32_e32 v66, v56, v57
	v_pk_mul_f32 v[60:61], v[38:39], v[54:55] op_sel:[0,1] op_sel_hi:[1,1]
	v_add_f32_e32 v134, v62, v63
	v_pk_fma_f32 v[58:59], v[2:3], v[32:33], v[58:59]
	v_add_f32_dpp v66, v66, v66 quad_perm:[1,0,3,2] row_mask:0xf bank_mask:0xf bound_ctrl:1
	v_pk_fma_f32 v[60:61], v[4:5], v[34:35], v[60:61]
	ds_read_b128 v[8:11], v73 offset:11520
	v_add_f32_dpp v66, v66, v66 quad_perm:[2,3,0,1] row_mask:0xf bank_mask:0xf bound_ctrl:1
	ds_read_b128 v[16:19], v73 offset:12032
	ds_read_b128 v[12:15], v73 offset:11776
	v_add_f32_dpp v66, v66, v66 row_half_mirror row_mask:0xf bank_mask:0xf bound_ctrl:1
	ds_read_b128 v[20:23], v73 offset:12288
	ds_read_b128 v[24:27], v73 offset:12544
	v_add_f32_dpp v66, v66, v66 row_mirror row_mask:0xf bank_mask:0xf bound_ctrl:1
	v_pk_fma_f32 v[2:3], v[40:41], v[66:67], v[58:59] op_sel_hi:[1,0,1]
	v_pk_fma_f32 v[4:5], v[42:43], v[66:67], v[60:61] op_sel_hi:[1,0,1]
	s_waitcnt lgkmcnt(5)
	v_pk_mul_f32 v[56:57], v[2:3], v[106:107]
	v_pk_mul_f32 v[62:63], v[2:3], v[44:45]
	v_pk_fma_f32 v[56:57], v[4:5], v[108:109], v[56:57]
	v_pk_fma_f32 v[62:63], v[4:5], v[46:47], v[62:63]
	v_pk_mul_f32 v[58:59], v[114:115], v[48:49] op_sel_hi:[1,0]
	v_add_f32_e32 v66, v56, v57
	v_pk_mul_f32 v[60:61], v[116:117], v[48:49] op_sel_hi:[1,0]
	v_add_f32_e32 v135, v62, v63
	v_pk_fma_f32 v[58:59], v[2:3], v[110:111], v[58:59]
	v_add_f32_dpp v66, v66, v66 quad_perm:[1,0,3,2] row_mask:0xf bank_mask:0xf bound_ctrl:1
	v_pk_fma_f32 v[60:61], v[4:5], v[112:113], v[60:61]
	v_cndmask_b32_e64 v136, v132, v133, s[50:51]
	ds_read_b128 v[28:31], v73 offset:12800
	v_add_f32_dpp v66, v66, v66 quad_perm:[2,3,0,1] row_mask:0xf bank_mask:0xf bound_ctrl:1
	ds_read_b128 v[36:39], v73 offset:13312
	v_cndmask_b32_e64 v137, v133, v132, s[50:51]
	ds_read_b128 v[32:35], v73 offset:13056
	v_add_f32_dpp v66, v66, v66 row_half_mirror row_mask:0xf bank_mask:0xf bound_ctrl:1
	ds_read_b128 v[40:43], v73 offset:13568
	v_cndmask_b32_e64 v138, v134, v135, s[50:51]
	ds_read_b128 v[44:47], v73 offset:13824
	v_add_f32_dpp v66, v66, v66 row_mirror row_mask:0xf bank_mask:0xf bound_ctrl:1
	v_cndmask_b32_e64 v139, v135, v134, s[50:51]
	v_pk_fma_f32 v[2:3], v[118:119], v[66:67], v[58:59] op_sel_hi:[1,0,1]
	v_pk_fma_f32 v[4:5], v[120:121], v[66:67], v[60:61] op_sel_hi:[1,0,1]
	s_waitcnt lgkmcnt(5)
; #define LAS __attribute__((address_space(3)))
; __device__ __forceinline__ void phase_scan(CParams& P, LAS unsigned char* lds) {
;     ...
;             f32x4 Ar0, Ar1, Aw0, Aw1, Ak0, Ak1, Aq0, Aq1, Ab0, Ab1, Br0, Br1, Bw0, Bw1, Bk0, Bk1, Bq0, Bq1, Bb0, Bb1; float Avv, Bvv;
; #pragma unroll 1
;             for (int c = 0; c < NCH; ++c) {
;                 __syncthreads();
;                 const LAS float* base = lf + (c & 1) * BUFF + 8 * oct;
;                 SC_LOAD(A, base);
; #pragma unroll 2
;                 for (int j = 0; j < CH; j += 2) { const LAS float* sp = base + j * STEPF;
;                     SC_LOAD(B, sp + STEPF); SC_STEP(A);
;                     SC_LOAD(A, sp + 2 * STEPF);
;                     SC_STEP(B); }
	v_pk_mul_f32 v[56:57], v[2:3], v[8:9]
	v_pk_mul_f32 v[62:63], v[2:3], v[122:123]
	v_pk_fma_f32 v[56:57], v[4:5], v[10:11], v[56:57]
	v_pk_fma_f32 v[62:63], v[4:5], v[124:125], v[62:63]
	v_pk_mul_f32 v[58:59], v[16:17], v[48:49] op_sel:[0,1] op_sel_hi:[1,1]
	v_add_f32_e32 v66, v56, v57
	v_pk_mul_f32 v[60:61], v[18:19], v[48:49] op_sel:[0,1] op_sel_hi:[1,1]
	v_add_f32_e32 v132, v62, v63
	v_pk_fma_f32 v[58:59], v[2:3], v[12:13], v[58:59]
	v_add_f32_dpp v66, v66, v66 quad_perm:[1,0,3,2] row_mask:0xf bank_mask:0xf bound_ctrl:1
	v_pk_fma_f32 v[60:61], v[4:5], v[14:15], v[60:61]
	v_add_f32_dpp v140, v137, v136 quad_perm:[1,0,3,2] row_mask:0xf bank_mask:0xf bound_ctrl:1
	ds_read_b128 v[106:109], v73 offset:14080
	v_add_f32_dpp v66, v66, v66 quad_perm:[2,3,0,1] row_mask:0xf bank_mask:0xf bound_ctrl:1
	ds_read_b128 v[114:117], v73 offset:14592
	v_add_f32_dpp v141, v139, v138 quad_perm:[1,0,3,2] row_mask:0xf bank_mask:0xf bound_ctrl:1
	ds_read_b128 v[110:113], v73 offset:14336
	v_add_f32_dpp v66, v66, v66 row_half_mirror row_mask:0xf bank_mask:0xf bound_ctrl:1
	ds_read_b128 v[118:121], v73 offset:14848
	v_cndmask_b32_e64 v142, v140, v141, s[52:53]
	ds_read_b128 v[122:125], v73 offset:15104
	v_add_f32_dpp v66, v66, v66 row_mirror row_mask:0xf bank_mask:0xf bound_ctrl:1
	ds_read_b128 v[52:55], v69 offset:48
	v_cndmask_b32_e64 v143, v141, v140, s[52:53]
	v_pk_fma_f32 v[2:3], v[20:21], v[66:67], v[58:59] op_sel_hi:[1,0,1]
	v_pk_fma_f32 v[4:5], v[22:23], v[66:67], v[60:61] op_sel_hi:[1,0,1]
	s_waitcnt lgkmcnt(6)
	v_pk_mul_f32 v[56:57], v[2:3], v[28:29]
	v_pk_mul_f32 v[62:63], v[2:3], v[24:25]
	v_pk_fma_f32 v[56:57], v[4:5], v[30:31], v[56:57]
	v_pk_fma_f32 v[62:63], v[4:5], v[26:27], v[62:63]
	v_pk_mul_f32 v[58:59], v[36:37], v[50:51] op_sel_hi:[1,0]
	v_add_f32_e32 v66, v56, v57
	v_pk_mul_f32 v[60:61], v[38:39], v[50:51] op_sel_hi:[1,0]
	v_add_f32_e32 v133, v62, v63
	v_pk_fma_f32 v[58:59], v[2:3], v[32:33], v[58:59]
	v_add_f32_dpp v66, v66, v66 quad_perm:[1,0,3,2] row_mask:0xf bank_mask:0xf bound_ctrl:1
	v_pk_fma_f32 v[60:61], v[4:5], v[34:35], v[60:61]
	v_add_f32_dpp v144, v143, v142 quad_perm:[2,3,0,1] row_mask:0xf bank_mask:0xf bound_ctrl:1
	ds_read_b128 v[8:11], v73 offset:15360
	v_add_f32_dpp v66, v66, v66 quad_perm:[2,3,0,1] row_mask:0xf bank_mask:0xf bound_ctrl:1
	ds_read_b128 v[16:19], v73 offset:15872
	v_add_f32_dpp v144, v144, v144 row_ror:4 row_mask:0xf bank_mask:0xf bound_ctrl:1
	ds_read_b128 v[12:15], v73 offset:15616
	v_add_f32_dpp v66, v66, v66 row_half_mirror row_mask:0xf bank_mask:0xf bound_ctrl:1
	ds_read_b128 v[20:23], v73 offset:16128
	v_add_f32_dpp v144, v144, v144 row_ror:8 row_mask:0xf bank_mask:0xf bound_ctrl:1
	ds_read_b128 v[24:27], v73 offset:16384
	v_add_f32_dpp v66, v66, v66 row_mirror row_mask:0xf bank_mask:0xf bound_ctrl:1
	global_store_dword v72, v144, s[10:11]
	v_add_u32_e32 v72, s13, v72
	v_pk_fma_f32 v[2:3], v[40:41], v[66:67], v[58:59] op_sel_hi:[1,0,1]
	v_pk_fma_f32 v[4:5], v[42:43], v[66:67], v[60:61] op_sel_hi:[1,0,1]
	s_waitcnt lgkmcnt(6)
	v_pk_mul_f32 v[56:57], v[2:3], v[106:107]
	v_pk_mul_f32 v[62:63], v[2:3], v[44:45]
	v_pk_fma_f32 v[56:57], v[4:5], v[108:109], v[56:57]
	v_pk_fma_f32 v[62:63], v[4:5], v[46:47], v[62:63]
	v_pk_mul_f32 v[58:59], v[114:115], v[50:51] op_sel:[0,1] op_sel_hi:[1,1]
	v_add_f32_e32 v66, v56, v57
	v_pk_mul_f32 v[60:61], v[116:117], v[50:51] op_sel:[0,1] op_sel_hi:[1,1]
	v_add_f32_e32 v134, v62, v63
	v_pk_fma_f32 v[58:59], v[2:3], v[110:111], v[58:59]
	v_add_f32_dpp v66, v66, v66 quad_perm:[1,0,3,2] row_mask:0xf bank_mask:0xf bound_ctrl:1
	v_pk_fma_f32 v[60:61], v[4:5], v[112:113], v[60:61]
	ds_read_b128 v[28:31], v73 offset:16640
	v_add_f32_dpp v66, v66, v66 quad_perm:[2,3,0,1] row_mask:0xf bank_mask:0xf bound_ctrl:1
	ds_read_b128 v[36:39], v73 offset:17152
	ds_read_b128 v[32:35], v73 offset:16896
	v_add_f32_dpp v66, v66, v66 row_half_mirror row_mask:0xf bank_mask:0xf bound_ctrl:1
	ds_read_b128 v[40:43], v73 offset:17408
	ds_read_b128 v[44:47], v73 offset:17664
	v_add_f32_dpp v66, v66, v66 row_mirror row_mask:0xf bank_mask:0xf bound_ctrl:1
	v_pk_fma_f32 v[2:3], v[118:119], v[66:67], v[58:59] op_sel_hi:[1,0,1]
	v_pk_fma_f32 v[4:5], v[120:121], v[66:67], v[60:61] op_sel_hi:[1,0,1]
	s_waitcnt lgkmcnt(5)
	v_pk_mul_f32 v[56:57], v[2:3], v[8:9]
	v_pk_mul_f32 v[62:63], v[2:3], v[122:123]
	v_pk_fma_f32 v[56:57], v[4:5], v[10:11], v[56:57]
	v_pk_fma_f32 v[62:63], v[4:5], v[124:125], v[62:63]
	v_pk_mul_f32 v[58:59], v[16:17], v[52:53] op_sel_hi:[1,0]
	v_add_f32_e32 v66, v56, v57
	v_pk_mul_f32 v[60:61], v[18:19], v[52:53] op_sel_hi:[1,0]
	v_add_f32_e32 v135, v62, v63
	v_pk_fma_f32 v[58:59], v[2:3], v[12:13], v[58:59]
	v_add_f32_dpp v66, v66, v66 quad_perm:[1,0,3,2] row_mask:0xf bank_mask:0xf bound_ctrl:1
	v_pk_fma_f32 v[60:61], v[4:5], v[14:15], v[60:61]
	v_cndmask_b32_e64 v136, v132, v133, s[50:51]
	ds_read_b128 v[106:109], v73 offset:17920
	v_add_f32_dpp v66, v66, v66 quad_perm:[2,3,0,1] row_mask:0xf bank_mask:0xf bound_ctrl:1
	ds_read_b128 v[114:117], v73 offset:18432
	v_cndmask_b32_e64 v137, v133, v132, s[50:51]
	ds_read_b128 v[110:113], v73 offset:18176
	v_add_f32_dpp v66, v66, v66 row_half_mirror row_mask:0xf bank_mask:0xf bound_ctrl:1
	ds_read_b128 v[118:121], v73 offset:18688
	v_cndmask_b32_e64 v138, v134, v135, s[50:51]
	ds_read_b128 v[122:125], v73 offset:18944
	v_add_f32_dpp v66, v66, v66 row_mirror row_mask:0xf bank_mask:0xf bound_ctrl:1
	v_cndmask_b32_e64 v139, v135, v134, s[50:51]
	v_pk_fma_f32 v[2:3], v[20:21], v[66:67], v[58:59] op_sel_hi:[1,0,1]
	v_pk_fma_f32 v[4:5], v[22:23], v[66:67], v[60:61] op_sel_hi:[1,0,1]
	s_waitcnt lgkmcnt(5)
; #define LAS __attribute__((address_space(3)))
; __device__ __forceinline__ void phase_scan(CParams& P, LAS unsigned char* lds) {
;     ...
;             f32x4 Ar0, Ar1, Aw0, Aw1, Ak0, Ak1, Aq0, Aq1, Ab0, Ab1, Br0, Br1, Bw0, Bw1, Bk0, Bk1, Bq0, Bq1, Bb0, Bb1; float Avv, Bvv;
; #pragma unroll 1
;             for (int c = 0; c < NCH; ++c) {
;                 __syncthreads();
;                 const LAS float* base = lf + (c & 1) * BUFF + 8 * oct;
;                 SC_LOAD(A, base);
; #pragma unroll 2
;                 for (int j = 0; j < CH; j += 2) { const LAS float* sp = base + j * STEPF;
;                     SC_LOAD(B, sp + STEPF); SC_STEP(A);
;                     SC_LOAD(A, sp + 2 * STEPF);
;                     SC_STEP(B); }
	v_pk_mul_f32 v[56:57], v[2:3], v[28:29]
	v_pk_mul_f32 v[62:63], v[2:3], v[24:25]
	v_pk_fma_f32 v[56:57], v[4:5], v[30:31], v[56:57]
	v_pk_fma_f32 v[62:63], v[4:5], v[26:27], v[62:63]
	v_pk_mul_f32 v[58:59], v[36:37], v[52:53] op_sel:[0,1] op_sel_hi:[1,1]
	v_add_f32_e32 v66, v56, v57
	v_pk_mul_f32 v[60:61], v[38:39], v[52:53] op_sel:[0,1] op_sel_hi:[1,1]
	v_add_f32_e32 v132, v62, v63
	v_pk_fma_f32 v[58:59], v[2:3], v[32:33], v[58:59]
	v_add_f32_dpp v66, v66, v66 quad_perm:[1,0,3,2] row_mask:0xf bank_mask:0xf bound_ctrl:1
	v_pk_fma_f32 v[60:61], v[4:5], v[34:35], v[60:61]
	v_add_f32_dpp v140, v137, v136 quad_perm:[1,0,3,2] row_mask:0xf bank_mask:0xf bound_ctrl:1
	ds_read_b128 v[8:11], v73 offset:19200
	v_add_f32_dpp v66, v66, v66 quad_perm:[2,3,0,1] row_mask:0xf bank_mask:0xf bound_ctrl:1
	ds_read_b128 v[16:19], v73 offset:19712
	v_add_f32_dpp v141, v139, v138 quad_perm:[1,0,3,2] row_mask:0xf bank_mask:0xf bound_ctrl:1
	ds_read_b128 v[12:15], v73 offset:19456
	v_add_f32_dpp v66, v66, v66 row_half_mirror row_mask:0xf bank_mask:0xf bound_ctrl:1
	ds_read_b128 v[20:23], v73 offset:19968
	v_cndmask_b32_e64 v142, v140, v141, s[52:53]
	ds_read_b128 v[24:27], v73 offset:20224
	v_add_f32_dpp v66, v66, v66 row_mirror row_mask:0xf bank_mask:0xf bound_ctrl:1
	ds_read_b128 v[48:51], v69 offset:64
	v_cndmask_b32_e64 v143, v141, v140, s[52:53]
	v_pk_fma_f32 v[2:3], v[40:41], v[66:67], v[58:59] op_sel_hi:[1,0,1]
	v_pk_fma_f32 v[4:5], v[42:43], v[66:67], v[60:61] op_sel_hi:[1,0,1]
	s_waitcnt lgkmcnt(6)
	v_pk_mul_f32 v[56:57], v[2:3], v[106:107]
	v_pk_mul_f32 v[62:63], v[2:3], v[44:45]
	v_pk_fma_f32 v[56:57], v[4:5], v[108:109], v[56:57]
	v_pk_fma_f32 v[62:63], v[4:5], v[46:47], v[62:63]
	v_pk_mul_f32 v[58:59], v[114:115], v[54:55] op_sel_hi:[1,0]
	v_add_f32_e32 v66, v56, v57
	v_pk_mul_f32 v[60:61], v[116:117], v[54:55] op_sel_hi:[1,0]
	v_add_f32_e32 v133, v62, v63
	v_pk_fma_f32 v[58:59], v[2:3], v[110:111], v[58:59]
	v_add_f32_dpp v66, v66, v66 quad_perm:[1,0,3,2] row_mask:0xf bank_mask:0xf bound_ctrl:1
	v_pk_fma_f32 v[60:61], v[4:5], v[112:113], v[60:61]
	v_add_f32_dpp v144, v143, v142 quad_perm:[2,3,0,1] row_mask:0xf bank_mask:0xf bound_ctrl:1
	ds_read_b128 v[28:31], v73 offset:20480
	v_add_f32_dpp v66, v66, v66 quad_perm:[2,3,0,1] row_mask:0xf bank_mask:0xf bound_ctrl:1
	ds_read_b128 v[36:39], v73 offset:20992
	v_add_f32_dpp v144, v144, v144 row_ror:4 row_mask:0xf bank_mask:0xf bound_ctrl:1
	ds_read_b128 v[32:35], v73 offset:20736
	v_add_f32_dpp v66, v66, v66 row_half_mirror row_mask:0xf bank_mask:0xf bound_ctrl:1
	ds_read_b128 v[40:43], v73 offset:21248
	v_add_f32_dpp v144, v144, v144 row_ror:8 row_mask:0xf bank_mask:0xf bound_ctrl:1
	ds_read_b128 v[44:47], v73 offset:21504
	v_add_f32_dpp v66, v66, v66 row_mirror row_mask:0xf bank_mask:0xf bound_ctrl:1
	global_store_dword v72, v144, s[10:11]
	v_add_u32_e32 v72, s13, v72
	v_pk_fma_f32 v[2:3], v[118:119], v[66:67], v[58:59] op_sel_hi:[1,0,1]
	v_pk_fma_f32 v[4:5], v[120:121], v[66:67], v[60:61] op_sel_hi:[1,0,1]
	s_waitcnt lgkmcnt(6)
	v_pk_mul_f32 v[56:57], v[2:3], v[8:9]
	v_pk_mul_f32 v[62:63], v[2:3], v[122:123]
	v_pk_fma_f32 v[56:57], v[4:5], v[10:11], v[56:57]
	v_pk_fma_f32 v[62:63], v[4:5], v[124:125], v[62:63]
	v_pk_mul_f32 v[58:59], v[16:17], v[54:55] op_sel:[0,1] op_sel_hi:[1,1]
	v_add_f32_e32 v66, v56, v57
	v_pk_mul_f32 v[60:61], v[18:19], v[54:55] op_sel:[0,1] op_sel_hi:[1,1]
	v_add_f32_e32 v134, v62, v63
	v_pk_fma_f32 v[58:59], v[2:3], v[12:13], v[58:59]
	v_add_f32_dpp v66, v66, v66 quad_perm:[1,0,3,2] row_mask:0xf bank_mask:0xf bound_ctrl:1
	v_pk_fma_f32 v[60:61], v[4:5], v[14:15], v[60:61]
	ds_read_b128 v[106:109], v73 offset:21760
	v_add_f32_dpp v66, v66, v66 quad_perm:[2,3,0,1] row_mask:0xf bank_mask:0xf bound_ctrl:1
	ds_read_b128 v[114:117], v73 offset:22272
	ds_read_b128 v[110:113], v73 offset:22016
	v_add_f32_dpp v66, v66, v66 row_half_mirror row_mask:0xf bank_mask:0xf bound_ctrl:1
	ds_read_b128 v[118:121], v73 offset:22528
	ds_read_b128 v[122:125], v73 offset:22784
	v_add_f32_dpp v66, v66, v66 row_mirror row_mask:0xf bank_mask:0xf bound_ctrl:1
	v_pk_fma_f32 v[2:3], v[20:21], v[66:67], v[58:59] op_sel_hi:[1,0,1]
	v_pk_fma_f32 v[4:5], v[22:23], v[66:67], v[60:61] op_sel_hi:[1,0,1]
	s_waitcnt lgkmcnt(5)
	v_pk_mul_f32 v[56:57], v[2:3], v[28:29]
	v_pk_mul_f32 v[62:63], v[2:3], v[24:25]
	v_pk_fma_f32 v[56:57], v[4:5], v[30:31], v[56:57]
	v_pk_fma_f32 v[62:63], v[4:5], v[26:27], v[62:63]
	v_pk_mul_f32 v[58:59], v[36:37], v[48:49] op_sel_hi:[1,0]
	v_add_f32_e32 v66, v56, v57
	v_pk_mul_f32 v[60:61], v[38:39], v[48:49] op_sel_hi:[1,0]
	v_add_f32_e32 v135, v62, v63
	v_pk_fma_f32 v[58:59], v[2:3], v[32:33], v[58:59]
	v_add_f32_dpp v66, v66, v66 quad_perm:[1,0,3,2] row_mask:0xf bank_mask:0xf bound_ctrl:1
	v_pk_fma_f32 v[60:61], v[4:5], v[34:35], v[60:61]
	v_cndmask_b32_e64 v136, v132, v133, s[50:51]
	ds_read_b128 v[8:11], v73 offset:23040
	v_add_f32_dpp v66, v66, v66 quad_perm:[2,3,0,1] row_mask:0xf bank_mask:0xf bound_ctrl:1
	ds_read_b128 v[16:19], v73 offset:23552
	v_cndmask_b32_e64 v137, v133, v132, s[50:51]
	ds_read_b128 v[12:15], v73 offset:23296
	v_add_f32_dpp v66, v66, v66 row_half_mirror row_mask:0xf bank_mask:0xf bound_ctrl:1
	ds_read_b128 v[20:23], v73 offset:23808
	v_cndmask_b32_e64 v138, v134, v135, s[50:51]
	ds_read_b128 v[24:27], v73 offset:24064
	v_add_f32_dpp v66, v66, v66 row_mirror row_mask:0xf bank_mask:0xf bound_ctrl:1
	v_cndmask_b32_e64 v139, v135, v134, s[50:51]
	v_pk_fma_f32 v[2:3], v[40:41], v[66:67], v[58:59] op_sel_hi:[1,0,1]
	v_pk_fma_f32 v[4:5], v[42:43], v[66:67], v[60:61] op_sel_hi:[1,0,1]
	s_waitcnt lgkmcnt(5)
; #define LAS __attribute__((address_space(3)))
; __device__ __forceinline__ void phase_scan(CParams& P, LAS unsigned char* lds) {
;     ...
;             f32x4 Ar0, Ar1, Aw0, Aw1, Ak0, Ak1, Aq0, Aq1, Ab0, Ab1, Br0, Br1, Bw0, Bw1, Bk0, Bk1, Bq0, Bq1, Bb0, Bb1; float Avv, Bvv;
; #pragma unroll 1
;             for (int c = 0; c < NCH; ++c) {
;                 __syncthreads();
;                 const LAS float* base = lf + (c & 1) * BUFF + 8 * oct;
;                 SC_LOAD(A, base);
; #pragma unroll 2
;                 for (int j = 0; j < CH; j += 2) { const LAS float* sp = base + j * STEPF;
;                     SC_LOAD(B, sp + STEPF); SC_STEP(A);
;                     SC_LOAD(A, sp + 2 * STEPF);
;                     SC_STEP(B); }
	v_pk_mul_f32 v[56:57], v[2:3], v[106:107]
	v_pk_mul_f32 v[62:63], v[2:3], v[44:45]
	v_pk_fma_f32 v[56:57], v[4:5], v[108:109], v[56:57]
	v_pk_fma_f32 v[62:63], v[4:5], v[46:47], v[62:63]
	v_pk_mul_f32 v[58:59], v[114:115], v[48:49] op_sel:[0,1] op_sel_hi:[1,1]
	v_add_f32_e32 v66, v56, v57
	v_pk_mul_f32 v[60:61], v[116:117], v[48:49] op_sel:[0,1] op_sel_hi:[1,1]
	v_add_f32_e32 v132, v62, v63
	v_pk_fma_f32 v[58:59], v[2:3], v[110:111], v[58:59]
	v_add_f32_dpp v66, v66, v66 quad_perm:[1,0,3,2] row_mask:0xf bank_mask:0xf bound_ctrl:1
	v_pk_fma_f32 v[60:61], v[4:5], v[112:113], v[60:61]
	v_add_f32_dpp v140, v137, v136 quad_perm:[1,0,3,2] row_mask:0xf bank_mask:0xf bound_ctrl:1
	ds_read_b128 v[28:31], v73 offset:24320
	v_add_f32_dpp v66, v66, v66 quad_perm:[2,3,0,1] row_mask:0xf bank_mask:0xf bound_ctrl:1
	ds_read_b128 v[36:39], v73 offset:24832
	v_add_f32_dpp v141, v139, v138 quad_perm:[1,0,3,2] row_mask:0xf bank_mask:0xf bound_ctrl:1
	ds_read_b128 v[32:35], v73 offset:24576
	v_add_f32_dpp v66, v66, v66 row_half_mirror row_mask:0xf bank_mask:0xf bound_ctrl:1
	ds_read_b128 v[40:43], v73 offset:25088
	v_cndmask_b32_e64 v142, v140, v141, s[52:53]
	ds_read_b128 v[44:47], v73 offset:25344
	v_add_f32_dpp v66, v66, v66 row_mirror row_mask:0xf bank_mask:0xf bound_ctrl:1
	ds_read_b128 v[52:55], v69 offset:80
	v_cndmask_b32_e64 v143, v141, v140, s[52:53]
	v_pk_fma_f32 v[2:3], v[118:119], v[66:67], v[58:59] op_sel_hi:[1,0,1]
	v_pk_fma_f32 v[4:5], v[120:121], v[66:67], v[60:61] op_sel_hi:[1,0,1]
	s_waitcnt lgkmcnt(6)
	v_pk_mul_f32 v[56:57], v[2:3], v[8:9]
	v_pk_mul_f32 v[62:63], v[2:3], v[122:123]
	v_pk_fma_f32 v[56:57], v[4:5], v[10:11], v[56:57]
	v_pk_fma_f32 v[62:63], v[4:5], v[124:125], v[62:63]
	v_pk_mul_f32 v[58:59], v[16:17], v[50:51] op_sel_hi:[1,0]
	v_add_f32_e32 v66, v56, v57
	v_pk_mul_f32 v[60:61], v[18:19], v[50:51] op_sel_hi:[1,0]
	v_add_f32_e32 v133, v62, v63
	v_pk_fma_f32 v[58:59], v[2:3], v[12:13], v[58:59]
	v_add_f32_dpp v66, v66, v66 quad_perm:[1,0,3,2] row_mask:0xf bank_mask:0xf bound_ctrl:1
	v_pk_fma_f32 v[60:61], v[4:5], v[14:15], v[60:61]
	v_add_f32_dpp v144, v143, v142 quad_perm:[2,3,0,1] row_mask:0xf bank_mask:0xf bound_ctrl:1
	ds_read_b128 v[106:109], v73 offset:25600
	v_add_f32_dpp v66, v66, v66 quad_perm:[2,3,0,1] row_mask:0xf bank_mask:0xf bound_ctrl:1
	ds_read_b128 v[114:117], v73 offset:26112
	v_add_f32_dpp v144, v144, v144 row_ror:4 row_mask:0xf bank_mask:0xf bound_ctrl:1
	ds_read_b128 v[110:113], v73 offset:25856
	v_add_f32_dpp v66, v66, v66 row_half_mirror row_mask:0xf bank_mask:0xf bound_ctrl:1
	ds_read_b128 v[118:121], v73 offset:26368
	v_add_f32_dpp v144, v144, v144 row_ror:8 row_mask:0xf bank_mask:0xf bound_ctrl:1
	ds_read_b128 v[122:125], v73 offset:26624
	v_add_f32_dpp v66, v66, v66 row_mirror row_mask:0xf bank_mask:0xf bound_ctrl:1
	global_store_dword v72, v144, s[10:11]
	v_add_u32_e32 v72, s13, v72
	v_pk_fma_f32 v[2:3], v[20:21], v[66:67], v[58:59] op_sel_hi:[1,0,1]
	v_pk_fma_f32 v[4:5], v[22:23], v[66:67], v[60:61] op_sel_hi:[1,0,1]
	s_waitcnt lgkmcnt(6)
	v_pk_mul_f32 v[56:57], v[2:3], v[28:29]
	v_pk_mul_f32 v[62:63], v[2:3], v[24:25]
	v_pk_fma_f32 v[56:57], v[4:5], v[30:31], v[56:57]
	v_pk_fma_f32 v[62:63], v[4:5], v[26:27], v[62:63]
	v_pk_mul_f32 v[58:59], v[36:37], v[50:51] op_sel:[0,1] op_sel_hi:[1,1]
	v_add_f32_e32 v66, v56, v57
	v_pk_mul_f32 v[60:61], v[38:39], v[50:51] op_sel:[0,1] op_sel_hi:[1,1]
	v_add_f32_e32 v134, v62, v63
	v_pk_fma_f32 v[58:59], v[2:3], v[32:33], v[58:59]
	v_add_f32_dpp v66, v66, v66 quad_perm:[1,0,3,2] row_mask:0xf bank_mask:0xf bound_ctrl:1
	v_pk_fma_f32 v[60:61], v[4:5], v[34:35], v[60:61]
	ds_read_b128 v[8:11], v73 offset:26880
	v_add_f32_dpp v66, v66, v66 quad_perm:[2,3,0,1] row_mask:0xf bank_mask:0xf bound_ctrl:1
	ds_read_b128 v[16:19], v73 offset:27392
	ds_read_b128 v[12:15], v73 offset:27136
	v_add_f32_dpp v66, v66, v66 row_half_mirror row_mask:0xf bank_mask:0xf bound_ctrl:1
	ds_read_b128 v[20:23], v73 offset:27648
	ds_read_b128 v[24:27], v73 offset:27904
	v_add_f32_dpp v66, v66, v66 row_mirror row_mask:0xf bank_mask:0xf bound_ctrl:1
	v_pk_fma_f32 v[2:3], v[40:41], v[66:67], v[58:59] op_sel_hi:[1,0,1]
	v_pk_fma_f32 v[4:5], v[42:43], v[66:67], v[60:61] op_sel_hi:[1,0,1]
	s_waitcnt lgkmcnt(5)
	v_pk_mul_f32 v[56:57], v[2:3], v[106:107]
	v_pk_mul_f32 v[62:63], v[2:3], v[44:45]
	v_pk_fma_f32 v[56:57], v[4:5], v[108:109], v[56:57]
	v_pk_fma_f32 v[62:63], v[4:5], v[46:47], v[62:63]
	v_pk_mul_f32 v[58:59], v[114:115], v[52:53] op_sel_hi:[1,0]
	v_add_f32_e32 v66, v56, v57
	v_pk_mul_f32 v[60:61], v[116:117], v[52:53] op_sel_hi:[1,0]
	v_add_f32_e32 v135, v62, v63
	v_pk_fma_f32 v[58:59], v[2:3], v[110:111], v[58:59]
	v_add_f32_dpp v66, v66, v66 quad_perm:[1,0,3,2] row_mask:0xf bank_mask:0xf bound_ctrl:1
	v_pk_fma_f32 v[60:61], v[4:5], v[112:113], v[60:61]
	v_cndmask_b32_e64 v136, v132, v133, s[50:51]
	ds_read_b128 v[28:31], v73 offset:28160
	v_add_f32_dpp v66, v66, v66 quad_perm:[2,3,0,1] row_mask:0xf bank_mask:0xf bound_ctrl:1
	ds_read_b128 v[36:39], v73 offset:28672
	v_cndmask_b32_e64 v137, v133, v132, s[50:51]
	ds_read_b128 v[32:35], v73 offset:28416
	v_add_f32_dpp v66, v66, v66 row_half_mirror row_mask:0xf bank_mask:0xf bound_ctrl:1
	ds_read_b128 v[40:43], v73 offset:28928
	v_cndmask_b32_e64 v138, v134, v135, s[50:51]
	ds_read_b128 v[44:47], v73 offset:29184
	v_add_f32_dpp v66, v66, v66 row_mirror row_mask:0xf bank_mask:0xf bound_ctrl:1
	v_cndmask_b32_e64 v139, v135, v134, s[50:51]
	v_pk_fma_f32 v[2:3], v[118:119], v[66:67], v[58:59] op_sel_hi:[1,0,1]
	v_pk_fma_f32 v[4:5], v[120:121], v[66:67], v[60:61] op_sel_hi:[1,0,1]
	s_waitcnt lgkmcnt(5)
; #define LAS __attribute__((address_space(3)))
; __device__ __forceinline__ void phase_scan(CParams& P, LAS unsigned char* lds) {
;     ...
;             f32x4 Ar0, Ar1, Aw0, Aw1, Ak0, Ak1, Aq0, Aq1, Ab0, Ab1, Br0, Br1, Bw0, Bw1, Bk0, Bk1, Bq0, Bq1, Bb0, Bb1; float Avv, Bvv;
; #pragma unroll 1
;             for (int c = 0; c < NCH; ++c) {
;                 __syncthreads();
;                 const LAS float* base = lf + (c & 1) * BUFF + 8 * oct;
;                 SC_LOAD(A, base);
; #pragma unroll 2
;                 for (int j = 0; j < CH; j += 2) { const LAS float* sp = base + j * STEPF;
;                     SC_LOAD(B, sp + STEPF); SC_STEP(A);
;                     SC_LOAD(A, sp + 2 * STEPF);
;                     SC_STEP(B); }
	v_pk_mul_f32 v[56:57], v[2:3], v[8:9]
	v_pk_mul_f32 v[62:63], v[2:3], v[122:123]
	v_pk_fma_f32 v[56:57], v[4:5], v[10:11], v[56:57]
	v_pk_fma_f32 v[62:63], v[4:5], v[124:125], v[62:63]
	v_pk_mul_f32 v[58:59], v[16:17], v[52:53] op_sel:[0,1] op_sel_hi:[1,1]
	v_add_f32_e32 v66, v56, v57
	v_pk_mul_f32 v[60:61], v[18:19], v[52:53] op_sel:[0,1] op_sel_hi:[1,1]
	v_add_f32_e32 v132, v62, v63
	v_pk_fma_f32 v[58:59], v[2:3], v[12:13], v[58:59]
	v_add_f32_dpp v66, v66, v66 quad_perm:[1,0,3,2] row_mask:0xf bank_mask:0xf bound_ctrl:1
	v_pk_fma_f32 v[60:61], v[4:5], v[14:15], v[60:61]
	v_add_f32_dpp v140, v137, v136 quad_perm:[1,0,3,2] row_mask:0xf bank_mask:0xf bound_ctrl:1
	ds_read_b128 v[106:109], v73 offset:29440
	v_add_f32_dpp v66, v66, v66 quad_perm:[2,3,0,1] row_mask:0xf bank_mask:0xf bound_ctrl:1
	ds_read_b128 v[114:117], v73 offset:29952
	v_add_f32_dpp v141, v139, v138 quad_perm:[1,0,3,2] row_mask:0xf bank_mask:0xf bound_ctrl:1
	ds_read_b128 v[110:113], v73 offset:29696
	v_add_f32_dpp v66, v66, v66 row_half_mirror row_mask:0xf bank_mask:0xf bound_ctrl:1
	ds_read_b128 v[118:121], v73 offset:30208
	v_cndmask_b32_e64 v142, v140, v141, s[52:53]
	ds_read_b128 v[122:125], v73 offset:30464
	v_add_f32_dpp v66, v66, v66 row_mirror row_mask:0xf bank_mask:0xf bound_ctrl:1
	ds_read_b128 v[48:51], v69 offset:96
	v_cndmask_b32_e64 v143, v141, v140, s[52:53]
	v_pk_fma_f32 v[2:3], v[20:21], v[66:67], v[58:59] op_sel_hi:[1,0,1]
	v_pk_fma_f32 v[4:5], v[22:23], v[66:67], v[60:61] op_sel_hi:[1,0,1]
	s_waitcnt lgkmcnt(6)
	v_pk_mul_f32 v[56:57], v[2:3], v[28:29]
	v_pk_mul_f32 v[62:63], v[2:3], v[24:25]
	v_pk_fma_f32 v[56:57], v[4:5], v[30:31], v[56:57]
	v_pk_fma_f32 v[62:63], v[4:5], v[26:27], v[62:63]
	v_pk_mul_f32 v[58:59], v[36:37], v[54:55] op_sel_hi:[1,0]
	v_add_f32_e32 v66, v56, v57
	v_pk_mul_f32 v[60:61], v[38:39], v[54:55] op_sel_hi:[1,0]
	v_add_f32_e32 v133, v62, v63
	v_pk_fma_f32 v[58:59], v[2:3], v[32:33], v[58:59]
	v_add_f32_dpp v66, v66, v66 quad_perm:[1,0,3,2] row_mask:0xf bank_mask:0xf bound_ctrl:1
	v_pk_fma_f32 v[60:61], v[4:5], v[34:35], v[60:61]
	v_add_f32_dpp v144, v143, v142 quad_perm:[2,3,0,1] row_mask:0xf bank_mask:0xf bound_ctrl:1
	ds_read_b128 v[8:11], v73 offset:30720
	v_add_f32_dpp v66, v66, v66 quad_perm:[2,3,0,1] row_mask:0xf bank_mask:0xf bound_ctrl:1
	ds_read_b128 v[16:19], v73 offset:31232
	v_add_f32_dpp v144, v144, v144 row_ror:4 row_mask:0xf bank_mask:0xf bound_ctrl:1
	ds_read_b128 v[12:15], v73 offset:30976
	v_add_f32_dpp v66, v66, v66 row_half_mirror row_mask:0xf bank_mask:0xf bound_ctrl:1
	ds_read_b128 v[20:23], v73 offset:31488
	v_add_f32_dpp v144, v144, v144 row_ror:8 row_mask:0xf bank_mask:0xf bound_ctrl:1
	ds_read_b128 v[24:27], v73 offset:31744
	v_add_f32_dpp v66, v66, v66 row_mirror row_mask:0xf bank_mask:0xf bound_ctrl:1
	global_store_dword v72, v144, s[10:11]
	v_add_u32_e32 v72, s13, v72
	v_pk_fma_f32 v[2:3], v[40:41], v[66:67], v[58:59] op_sel_hi:[1,0,1]
	v_pk_fma_f32 v[4:5], v[42:43], v[66:67], v[60:61] op_sel_hi:[1,0,1]
	s_waitcnt lgkmcnt(6)
	v_pk_mul_f32 v[56:57], v[2:3], v[106:107]
	v_pk_mul_f32 v[62:63], v[2:3], v[44:45]
	v_pk_fma_f32 v[56:57], v[4:5], v[108:109], v[56:57]
	v_pk_fma_f32 v[62:63], v[4:5], v[46:47], v[62:63]
	v_pk_mul_f32 v[58:59], v[114:115], v[54:55] op_sel:[0,1] op_sel_hi:[1,1]
	v_add_f32_e32 v66, v56, v57
	v_pk_mul_f32 v[60:61], v[116:117], v[54:55] op_sel:[0,1] op_sel_hi:[1,1]
	v_add_f32_e32 v134, v62, v63
	v_pk_fma_f32 v[58:59], v[2:3], v[110:111], v[58:59]
	v_add_f32_dpp v66, v66, v66 quad_perm:[1,0,3,2] row_mask:0xf bank_mask:0xf bound_ctrl:1
	v_pk_fma_f32 v[60:61], v[4:5], v[112:113], v[60:61]
	ds_read_b128 v[28:31], v73 offset:32000
	v_add_f32_dpp v66, v66, v66 quad_perm:[2,3,0,1] row_mask:0xf bank_mask:0xf bound_ctrl:1
	ds_read_b128 v[36:39], v73 offset:32512
	ds_read_b128 v[32:35], v73 offset:32256
	v_add_f32_dpp v66, v66, v66 row_half_mirror row_mask:0xf bank_mask:0xf bound_ctrl:1
	ds_read_b128 v[40:43], v73 offset:32768
	ds_read_b128 v[44:47], v73 offset:33024
	v_add_f32_dpp v66, v66, v66 row_mirror row_mask:0xf bank_mask:0xf bound_ctrl:1
	v_pk_fma_f32 v[2:3], v[118:119], v[66:67], v[58:59] op_sel_hi:[1,0,1]
	v_pk_fma_f32 v[4:5], v[120:121], v[66:67], v[60:61] op_sel_hi:[1,0,1]
	s_waitcnt lgkmcnt(5)
	v_pk_mul_f32 v[56:57], v[2:3], v[8:9]
	v_pk_mul_f32 v[62:63], v[2:3], v[122:123]
	v_pk_fma_f32 v[56:57], v[4:5], v[10:11], v[56:57]
	v_pk_fma_f32 v[62:63], v[4:5], v[124:125], v[62:63]
	v_pk_mul_f32 v[58:59], v[16:17], v[48:49] op_sel_hi:[1,0]
	v_add_f32_e32 v66, v56, v57
	v_pk_mul_f32 v[60:61], v[18:19], v[48:49] op_sel_hi:[1,0]
	v_add_f32_e32 v135, v62, v63
	v_pk_fma_f32 v[58:59], v[2:3], v[12:13], v[58:59]
	v_add_f32_dpp v66, v66, v66 quad_perm:[1,0,3,2] row_mask:0xf bank_mask:0xf bound_ctrl:1
	v_pk_fma_f32 v[60:61], v[4:5], v[14:15], v[60:61]
	v_cndmask_b32_e64 v136, v132, v133, s[50:51]
	ds_read_b128 v[106:109], v73 offset:33280
	v_add_f32_dpp v66, v66, v66 quad_perm:[2,3,0,1] row_mask:0xf bank_mask:0xf bound_ctrl:1
	ds_read_b128 v[114:117], v73 offset:33792
	v_cndmask_b32_e64 v137, v133, v132, s[50:51]
	ds_read_b128 v[110:113], v73 offset:33536
	v_add_f32_dpp v66, v66, v66 row_half_mirror row_mask:0xf bank_mask:0xf bound_ctrl:1
	ds_read_b128 v[118:121], v73 offset:34048
	v_cndmask_b32_e64 v138, v134, v135, s[50:51]
	ds_read_b128 v[122:125], v73 offset:34304
	v_add_f32_dpp v66, v66, v66 row_mirror row_mask:0xf bank_mask:0xf bound_ctrl:1
	v_cndmask_b32_e64 v139, v135, v134, s[50:51]
	v_pk_fma_f32 v[2:3], v[20:21], v[66:67], v[58:59] op_sel_hi:[1,0,1]
	v_pk_fma_f32 v[4:5], v[22:23], v[66:67], v[60:61] op_sel_hi:[1,0,1]
	s_waitcnt lgkmcnt(5)
; #define LAS __attribute__((address_space(3)))
; __device__ __forceinline__ void phase_scan(CParams& P, LAS unsigned char* lds) {
;     ...
;             f32x4 Ar0, Ar1, Aw0, Aw1, Ak0, Ak1, Aq0, Aq1, Ab0, Ab1, Br0, Br1, Bw0, Bw1, Bk0, Bk1, Bq0, Bq1, Bb0, Bb1; float Avv, Bvv;
; #pragma unroll 1
;             for (int c = 0; c < NCH; ++c) {
;                 __syncthreads();
;                 const LAS float* base = lf + (c & 1) * BUFF + 8 * oct;
;                 SC_LOAD(A, base);
; #pragma unroll 2
;                 for (int j = 0; j < CH; j += 2) { const LAS float* sp = base + j * STEPF;
;                     SC_LOAD(B, sp + STEPF); SC_STEP(A);
;                     SC_LOAD(A, sp + 2 * STEPF);
;                     SC_STEP(B); }
	v_pk_mul_f32 v[56:57], v[2:3], v[28:29]
	v_pk_mul_f32 v[62:63], v[2:3], v[24:25]
	v_pk_fma_f32 v[56:57], v[4:5], v[30:31], v[56:57]
	v_pk_fma_f32 v[62:63], v[4:5], v[26:27], v[62:63]
	v_pk_mul_f32 v[58:59], v[36:37], v[48:49] op_sel:[0,1] op_sel_hi:[1,1]
	v_add_f32_e32 v66, v56, v57
	v_pk_mul_f32 v[60:61], v[38:39], v[48:49] op_sel:[0,1] op_sel_hi:[1,1]
	v_add_f32_e32 v132, v62, v63
	v_pk_fma_f32 v[58:59], v[2:3], v[32:33], v[58:59]
	v_add_f32_dpp v66, v66, v66 quad_perm:[1,0,3,2] row_mask:0xf bank_mask:0xf bound_ctrl:1
	v_pk_fma_f32 v[60:61], v[4:5], v[34:35], v[60:61]
	v_add_f32_dpp v140, v137, v136 quad_perm:[1,0,3,2] row_mask:0xf bank_mask:0xf bound_ctrl:1
	ds_read_b128 v[8:11], v73 offset:34560
	v_add_f32_dpp v66, v66, v66 quad_perm:[2,3,0,1] row_mask:0xf bank_mask:0xf bound_ctrl:1
	ds_read_b128 v[16:19], v73 offset:35072
	v_add_f32_dpp v141, v139, v138 quad_perm:[1,0,3,2] row_mask:0xf bank_mask:0xf bound_ctrl:1
	ds_read_b128 v[12:15], v73 offset:34816
	v_add_f32_dpp v66, v66, v66 row_half_mirror row_mask:0xf bank_mask:0xf bound_ctrl:1
	ds_read_b128 v[20:23], v73 offset:35328
	v_cndmask_b32_e64 v142, v140, v141, s[52:53]
	ds_read_b128 v[24:27], v73 offset:35584
	v_add_f32_dpp v66, v66, v66 row_mirror row_mask:0xf bank_mask:0xf bound_ctrl:1
	ds_read_b128 v[52:55], v69 offset:112
	v_cndmask_b32_e64 v143, v141, v140, s[52:53]
	v_pk_fma_f32 v[2:3], v[40:41], v[66:67], v[58:59] op_sel_hi:[1,0,1]
	v_pk_fma_f32 v[4:5], v[42:43], v[66:67], v[60:61] op_sel_hi:[1,0,1]
	s_waitcnt lgkmcnt(6)
	v_pk_mul_f32 v[56:57], v[2:3], v[106:107]
	v_pk_mul_f32 v[62:63], v[2:3], v[44:45]
	v_pk_fma_f32 v[56:57], v[4:5], v[108:109], v[56:57]
	v_pk_fma_f32 v[62:63], v[4:5], v[46:47], v[62:63]
	v_pk_mul_f32 v[58:59], v[114:115], v[50:51] op_sel_hi:[1,0]
	v_add_f32_e32 v66, v56, v57
	v_pk_mul_f32 v[60:61], v[116:117], v[50:51] op_sel_hi:[1,0]
	v_add_f32_e32 v133, v62, v63
	v_pk_fma_f32 v[58:59], v[2:3], v[110:111], v[58:59]
	v_add_f32_dpp v66, v66, v66 quad_perm:[1,0,3,2] row_mask:0xf bank_mask:0xf bound_ctrl:1
	v_pk_fma_f32 v[60:61], v[4:5], v[112:113], v[60:61]
	v_add_f32_dpp v144, v143, v142 quad_perm:[2,3,0,1] row_mask:0xf bank_mask:0xf bound_ctrl:1
	ds_read_b128 v[28:31], v73 offset:35840
	v_add_f32_dpp v66, v66, v66 quad_perm:[2,3,0,1] row_mask:0xf bank_mask:0xf bound_ctrl:1
	ds_read_b128 v[36:39], v73 offset:36352
	v_add_f32_dpp v144, v144, v144 row_ror:4 row_mask:0xf bank_mask:0xf bound_ctrl:1
	ds_read_b128 v[32:35], v73 offset:36096
	v_add_f32_dpp v66, v66, v66 row_half_mirror row_mask:0xf bank_mask:0xf bound_ctrl:1
	ds_read_b128 v[40:43], v73 offset:36608
	v_add_f32_dpp v144, v144, v144 row_ror:8 row_mask:0xf bank_mask:0xf bound_ctrl:1
	ds_read_b128 v[44:47], v73 offset:36864
	v_add_f32_dpp v66, v66, v66 row_mirror row_mask:0xf bank_mask:0xf bound_ctrl:1
	global_store_dword v72, v144, s[10:11]
	v_add_u32_e32 v72, s13, v72
	v_pk_fma_f32 v[2:3], v[118:119], v[66:67], v[58:59] op_sel_hi:[1,0,1]
	v_pk_fma_f32 v[4:5], v[120:121], v[66:67], v[60:61] op_sel_hi:[1,0,1]
	s_waitcnt lgkmcnt(6)
	v_pk_mul_f32 v[56:57], v[2:3], v[8:9]
	v_pk_mul_f32 v[62:63], v[2:3], v[122:123]
	v_pk_fma_f32 v[56:57], v[4:5], v[10:11], v[56:57]
	v_pk_fma_f32 v[62:63], v[4:5], v[124:125], v[62:63]
	v_pk_mul_f32 v[58:59], v[16:17], v[50:51] op_sel:[0,1] op_sel_hi:[1,1]
	v_add_f32_e32 v66, v56, v57
	v_pk_mul_f32 v[60:61], v[18:19], v[50:51] op_sel:[0,1] op_sel_hi:[1,1]
	v_add_f32_e32 v134, v62, v63
	v_pk_fma_f32 v[58:59], v[2:3], v[12:13], v[58:59]
	v_add_f32_dpp v66, v66, v66 quad_perm:[1,0,3,2] row_mask:0xf bank_mask:0xf bound_ctrl:1
	v_pk_fma_f32 v[60:61], v[4:5], v[14:15], v[60:61]
	ds_read_b128 v[106:109], v73 offset:37120
	v_add_f32_dpp v66, v66, v66 quad_perm:[2,3,0,1] row_mask:0xf bank_mask:0xf bound_ctrl:1
	ds_read_b128 v[114:117], v73 offset:37632
	ds_read_b128 v[110:113], v73 offset:37376
	v_add_f32_dpp v66, v66, v66 row_half_mirror row_mask:0xf bank_mask:0xf bound_ctrl:1
	ds_read_b128 v[118:121], v73 offset:37888
	ds_read_b128 v[122:125], v73 offset:38144
	v_add_f32_dpp v66, v66, v66 row_mirror row_mask:0xf bank_mask:0xf bound_ctrl:1
	v_pk_fma_f32 v[2:3], v[20:21], v[66:67], v[58:59] op_sel_hi:[1,0,1]
	v_pk_fma_f32 v[4:5], v[22:23], v[66:67], v[60:61] op_sel_hi:[1,0,1]
	s_waitcnt lgkmcnt(5)
	v_pk_mul_f32 v[56:57], v[2:3], v[28:29]
	v_pk_mul_f32 v[62:63], v[2:3], v[24:25]
	v_pk_fma_f32 v[56:57], v[4:5], v[30:31], v[56:57]
	v_pk_fma_f32 v[62:63], v[4:5], v[26:27], v[62:63]
	v_pk_mul_f32 v[58:59], v[36:37], v[52:53] op_sel_hi:[1,0]
	v_add_f32_e32 v66, v56, v57
	v_pk_mul_f32 v[60:61], v[38:39], v[52:53] op_sel_hi:[1,0]
	v_add_f32_e32 v135, v62, v63
	v_pk_fma_f32 v[58:59], v[2:3], v[32:33], v[58:59]
	v_add_f32_dpp v66, v66, v66 quad_perm:[1,0,3,2] row_mask:0xf bank_mask:0xf bound_ctrl:1
	v_pk_fma_f32 v[60:61], v[4:5], v[34:35], v[60:61]
	v_cndmask_b32_e64 v136, v132, v133, s[50:51]
	ds_read_b128 v[8:11], v73 offset:38400
	v_add_f32_dpp v66, v66, v66 quad_perm:[2,3,0,1] row_mask:0xf bank_mask:0xf bound_ctrl:1
	ds_read_b128 v[16:19], v73 offset:38912
	v_cndmask_b32_e64 v137, v133, v132, s[50:51]
	ds_read_b128 v[12:15], v73 offset:38656
	v_add_f32_dpp v66, v66, v66 row_half_mirror row_mask:0xf bank_mask:0xf bound_ctrl:1
	ds_read_b128 v[20:23], v73 offset:39168
	v_cndmask_b32_e64 v138, v134, v135, s[50:51]
	ds_read_b128 v[24:27], v73 offset:39424
	v_add_f32_dpp v66, v66, v66 row_mirror row_mask:0xf bank_mask:0xf bound_ctrl:1
	v_cndmask_b32_e64 v139, v135, v134, s[50:51]
	v_pk_fma_f32 v[2:3], v[40:41], v[66:67], v[58:59] op_sel_hi:[1,0,1]
	v_pk_fma_f32 v[4:5], v[42:43], v[66:67], v[60:61] op_sel_hi:[1,0,1]
	s_waitcnt lgkmcnt(5)
; #define LAS __attribute__((address_space(3)))
; __device__ __forceinline__ void phase_scan(CParams& P, LAS unsigned char* lds) {
;     ...
;             for (int c = 0; c < NCH; ++c) {
;                 __syncthreads();
;                 const LAS float* base = lf + (c & 1) * BUFF + 8 * oct;
;                 SC_LOAD(A, base);
; #pragma unroll 2
;                 for (int j = 0; j < CH; j += 2) { const LAS float* sp = base + j * STEPF;
;                     SC_LOAD(B, sp + STEPF); SC_STEP(A);
;                     SC_LOAD(A, sp + 2 * STEPF);
;                     SC_STEP(B); }
;             }
	v_pk_mul_f32 v[56:57], v[2:3], v[106:107]
	v_pk_mul_f32 v[62:63], v[2:3], v[44:45]
	v_pk_fma_f32 v[56:57], v[4:5], v[108:109], v[56:57]
	v_pk_fma_f32 v[62:63], v[4:5], v[46:47], v[62:63]
	v_pk_mul_f32 v[58:59], v[114:115], v[52:53] op_sel:[0,1] op_sel_hi:[1,1]
	v_add_f32_e32 v66, v56, v57
	v_pk_mul_f32 v[60:61], v[116:117], v[52:53] op_sel:[0,1] op_sel_hi:[1,1]
	v_add_f32_e32 v132, v62, v63
	v_pk_fma_f32 v[58:59], v[2:3], v[110:111], v[58:59]
	v_add_f32_dpp v66, v66, v66 quad_perm:[1,0,3,2] row_mask:0xf bank_mask:0xf bound_ctrl:1
	v_pk_fma_f32 v[60:61], v[4:5], v[112:113], v[60:61]
	v_add_f32_dpp v140, v137, v136 quad_perm:[1,0,3,2] row_mask:0xf bank_mask:0xf bound_ctrl:1
	ds_read_b128 v[28:31], v73 offset:39680
	v_add_f32_dpp v66, v66, v66 quad_perm:[2,3,0,1] row_mask:0xf bank_mask:0xf bound_ctrl:1
	ds_read_b128 v[36:39], v73 offset:40192
	v_add_f32_dpp v141, v139, v138 quad_perm:[1,0,3,2] row_mask:0xf bank_mask:0xf bound_ctrl:1
	ds_read_b128 v[32:35], v73 offset:39936
	v_add_f32_dpp v66, v66, v66 row_half_mirror row_mask:0xf bank_mask:0xf bound_ctrl:1
	ds_read_b128 v[40:43], v73 offset:40448
	v_cndmask_b32_e64 v142, v140, v141, s[52:53]
	ds_read_b128 v[44:47], v73 offset:40704
	v_add_f32_dpp v66, v66, v66 row_mirror row_mask:0xf bank_mask:0xf bound_ctrl:1
	v_cndmask_b32_e64 v143, v141, v140, s[52:53]
	v_pk_fma_f32 v[2:3], v[118:119], v[66:67], v[58:59] op_sel_hi:[1,0,1]
	v_pk_fma_f32 v[4:5], v[120:121], v[66:67], v[60:61] op_sel_hi:[1,0,1]
	s_waitcnt lgkmcnt(5)
	v_pk_mul_f32 v[56:57], v[2:3], v[8:9]
	v_pk_mul_f32 v[62:63], v[2:3], v[122:123]
	v_pk_fma_f32 v[56:57], v[4:5], v[10:11], v[56:57]
	v_pk_fma_f32 v[62:63], v[4:5], v[124:125], v[62:63]
	v_pk_mul_f32 v[58:59], v[16:17], v[54:55] op_sel_hi:[1,0]
	v_add_f32_e32 v66, v56, v57
	v_pk_mul_f32 v[60:61], v[18:19], v[54:55] op_sel_hi:[1,0]
	v_add_f32_e32 v133, v62, v63
	v_pk_fma_f32 v[58:59], v[2:3], v[12:13], v[58:59]
	v_add_f32_dpp v66, v66, v66 quad_perm:[1,0,3,2] row_mask:0xf bank_mask:0xf bound_ctrl:1
	v_pk_fma_f32 v[60:61], v[4:5], v[14:15], v[60:61]
	v_add_f32_dpp v144, v143, v142 quad_perm:[2,3,0,1] row_mask:0xf bank_mask:0xf bound_ctrl:1
	v_add_f32_dpp v66, v66, v66 quad_perm:[2,3,0,1] row_mask:0xf bank_mask:0xf bound_ctrl:1
	s_nop 0
	v_add_f32_dpp v144, v144, v144 row_ror:4 row_mask:0xf bank_mask:0xf bound_ctrl:1
	v_add_f32_dpp v66, v66, v66 row_half_mirror row_mask:0xf bank_mask:0xf bound_ctrl:1
	s_nop 0
	v_add_f32_dpp v144, v144, v144 row_ror:8 row_mask:0xf bank_mask:0xf bound_ctrl:1
	v_add_f32_dpp v66, v66, v66 row_mirror row_mask:0xf bank_mask:0xf bound_ctrl:1
	global_store_dword v72, v144, s[10:11]
	v_add_u32_e32 v72, s13, v72
	v_pk_fma_f32 v[2:3], v[20:21], v[66:67], v[58:59] op_sel_hi:[1,0,1]
	v_pk_fma_f32 v[4:5], v[22:23], v[66:67], v[60:61] op_sel_hi:[1,0,1]
	s_waitcnt lgkmcnt(0)
	v_pk_mul_f32 v[56:57], v[2:3], v[28:29]
	v_pk_mul_f32 v[62:63], v[2:3], v[24:25]
	v_pk_fma_f32 v[56:57], v[4:5], v[30:31], v[56:57]
	v_pk_fma_f32 v[62:63], v[4:5], v[26:27], v[62:63]
	v_pk_mul_f32 v[58:59], v[36:37], v[54:55] op_sel:[0,1] op_sel_hi:[1,1]
	v_add_f32_e32 v66, v56, v57
	v_pk_mul_f32 v[60:61], v[38:39], v[54:55] op_sel:[0,1] op_sel_hi:[1,1]
	v_add_f32_e32 v134, v62, v63
	v_pk_fma_f32 v[58:59], v[2:3], v[32:33], v[58:59]
	v_add_f32_dpp v66, v66, v66 quad_perm:[1,0,3,2] row_mask:0xf bank_mask:0xf bound_ctrl:1
	v_pk_fma_f32 v[60:61], v[4:5], v[34:35], v[60:61]
	s_nop 0
	v_add_f32_dpp v66, v66, v66 quad_perm:[2,3,0,1] row_mask:0xf bank_mask:0xf bound_ctrl:1
	s_nop 1
	v_add_f32_dpp v66, v66, v66 row_half_mirror row_mask:0xf bank_mask:0xf bound_ctrl:1
	s_nop 1
	v_add_f32_dpp v66, v66, v66 row_mirror row_mask:0xf bank_mask:0xf bound_ctrl:1
	v_pk_fma_f32 v[2:3], v[40:41], v[66:67], v[58:59] op_sel_hi:[1,0,1]
	v_pk_fma_f32 v[4:5], v[42:43], v[66:67], v[60:61] op_sel_hi:[1,0,1]
	v_pk_mul_f32 v[62:63], v[2:3], v[44:45]
	v_pk_fma_f32 v[62:63], v[4:5], v[46:47], v[62:63]
	v_add_f32_e32 v135, v62, v63
	v_cndmask_b32_e64 v136, v132, v133, s[50:51]
	v_cndmask_b32_e64 v137, v133, v132, s[50:51]
	v_cndmask_b32_e64 v138, v134, v135, s[50:51]
	v_cndmask_b32_e64 v139, v135, v134, s[50:51]
	v_add_f32_dpp v140, v137, v136 quad_perm:[1,0,3,2] row_mask:0xf bank_mask:0xf bound_ctrl:1
	s_nop 0
	v_add_f32_dpp v141, v139, v138 quad_perm:[1,0,3,2] row_mask:0xf bank_mask:0xf bound_ctrl:1
	v_cndmask_b32_e64 v142, v140, v141, s[52:53]
	v_cndmask_b32_e64 v143, v141, v140, s[52:53]
	s_nop 1
	v_add_f32_dpp v144, v143, v142 quad_perm:[2,3,0,1] row_mask:0xf bank_mask:0xf bound_ctrl:1
	s_nop 1
	v_add_f32_dpp v144, v144, v144 row_ror:4 row_mask:0xf bank_mask:0xf bound_ctrl:1
	s_nop 1
	v_add_f32_dpp v144, v144, v144 row_ror:8 row_mask:0xf bank_mask:0xf bound_ctrl:1
	global_store_dword v72, v144, s[10:11]
	v_add_u32_e32 v72, s13, v72
	s_xor_b32 s14, s14, 0xb000
	s_add_i32 s12, s12, 1
	s_cmp_lt_u32 s12, 0x80
	s_cbranch_scc1 .Lsc_chunk
